# v12 plus HGRN output phase: the four per-token IEEE rsqrt sequences computed once per lane and broadcast within the quad by DPP (bit-identical)
# speedup vs baseline: 1.0115x; 1.0098x over previous
; #define LAS __attribute__((address_space(3)))
; __device__ __forceinline__ unsigned f2bf(float f) { return pk2(f, 0.f) & 0xffffu; }
; __device__ __forceinline__ float row16_sum(float x) { x += dpp_f<0xB1>(x); x += dpp_f<0x4E>(x); x += dpp_f<0x141>(x); x += dpp_f<0x140>(x); return x; }
; __device__ __forceinline__ void hg_out(const bf16* QT, const bf16* KTL, const bf16* KT, const bf16* IV, const float* DB, const float* SL, const float* DT, const float* norm_g, bf16* SGO, LAS unsigned char* lds) {
;     ...
;             for (int kt = 0; kt < 8; ++kt) { S[kt] = __builtin_amdgcn_mfma_f32_16x16x32_bf16(mk8(ktv[kt].x, ktv[kt].y, 0u, 0u), vb, S[kt], 0, 0, 0); S[kt] = S[kt] * dv[kt]; }
;             LAS float* sb_ = ssb + (ci & 1) * 128;
; #pragma unroll
;             for (int i = 0; i < 4; ++i) { const float ss = row16_sum(o[i] * o[i]); if (fr == 0) sb_[(4 * fq + i) * 8 + w] = ss; }
;             __syncthreads();
;             const float sgv[4] = {sg0, sg1, sg2, sg3};
; #pragma unroll
;             for (int i = 0; i < 4; ++i) {
;                 const f32x4 a0 = *(const LAS f32x4*)(sb_ + (4 * fq + i) * 8), a1 = *(const LAS f32x4*)(sb_ + (4 * fq + i) * 8 + 4);
;                 const float tot = ((a0[0] + a0[1]) + (a0[2] + a0[3])) + ((a1[0] + a1[1]) + (a1[2] + a1[3]));
;                 const float r = 1.0f / sqrtf(tot * (1.0f / 128.0f) + 1e-6f);
;                 gp[(size_t)i * 1024] = (bf16)f2bf(o[i] * r * ng * sgv[i]);
;             }
.LBB0_2134:
	s_or_b64 exec, exec, s[54:55]
	v_pk_mul_f32 v[6:7], v[50:51], v[94:95]
	v_add_u32_e32 v50, s60, v125
	s_waitcnt lgkmcnt(0)
	s_barrier
	v_and_b32_e32 v34, 3, v230
	v_lshl_add_u32 v34, v34, 5, v50
	ds_read_b128 v[24:27], v34
	ds_read_b128 v[28:31], v34 offset:16
	v_lshl_add_u64 v[0:1], v[118:119], 0, s[48:49]
	v_pk_mul_f32 v[16:17], v[44:45], v[100:101]
	v_pk_mul_f32 v[18:19], v[46:47], v[102:103]
	s_waitcnt lgkmcnt(1)
	v_add_f32_e32 v24, v24, v25
	v_add_f32_e32 v25, v26, v27
	v_add_f32_e32 v24, v24, v25
	s_waitcnt lgkmcnt(0)
	v_add_f32_e32 v25, v28, v29
	v_add_f32_e32 v26, v30, v31
	v_add_f32_e32 v25, v25, v26
	v_add_f32_e32 v24, v24, v25
	v_fmamk_f32 v24, v24, 0x3c000000, v228
	v_mul_f32_e32 v25, 0x4f800000, v24
	v_cmp_gt_f32_e32 vcc, s24, v24
	s_waitcnt vmcnt(25)
	v_pk_mul_f32 v[30:31], v[42:43], v[90:91]
	v_pk_mul_f32 v[28:29], v[40:41], v[88:89]
	v_cndmask_b32_e32 v24, v24, v25, vcc
	v_sqrt_f32_e32 v25, v24
	s_waitcnt vmcnt(24)
	v_pk_mul_f32 v[26:27], v[38:39], v[86:87]
	v_or_b32_e32 v1, s17, v1
	v_or_b32_e32 v0, s16, v0
	v_add_u32_e32 v34, -1, v25
	v_fma_f32 v35, -v34, v25, v24
	v_cmp_ge_f32_e64 s[48:49], 0, v35
	v_add_u32_e32 v35, 1, v25
	v_lshlrev_b32_e32 v72, 16, v249
	v_cndmask_b32_e64 v34, v25, v34, s[48:49]
	v_fma_f32 v25, -v35, v25, v24
	v_cmp_lt_f32_e64 s[48:49], 0, v25
	v_lshlrev_b64 v[0:1], 11, v[0:1]
	v_lshl_add_u64 v[32:33], v[184:185], 0, v[0:1]
	v_cndmask_b32_e64 v25, v34, v35, s[48:49]
	v_mul_f32_e32 v34, 0x37800000, v25
	v_cndmask_b32_e32 v25, v25, v34, vcc
	v_cmp_class_f32_e32 vcc, v24, v229
	v_lshlrev_b32_e32 v74, 16, v250
	v_lshlrev_b32_e32 v73, 16, v248
	v_cndmask_b32_e32 v42, v25, v24, vcc
	v_div_scale_f32 v43, s[48:49], v42, v42, 1.0
	v_rcp_f32_e32 v44, v43
	v_pk_mul_f32 v[24:25], v[36:37], v[84:85]
	v_lshlrev_b32_e32 v75, 16, v247
	v_fma_f32 v45, -v43, v44, 1.0
	v_fmac_f32_e32 v44, v45, v44
	v_div_scale_f32 v45, vcc, 1.0, v42, 1.0
	v_mul_f32_e32 v46, v45, v44
	v_fma_f32 v47, -v43, v46, v45
	v_fmac_f32_e32 v46, v47, v44
	v_fma_f32 v43, -v43, v46, v45
	s_nop 0
	v_div_fmas_f32 v43, v43, v44, v46
	v_div_fixup_f32 v36, v43, v42, 1.0
	v_pk_mul_f32 v[22:23], v[66:67], v[98:99]
	v_pk_mul_f32 v[20:21], v[64:65], v[96:97]
	v_mov_b32_dpp v34, v36 quad_perm:[0,0,0,0] row_mask:0xf bank_mask:0xf
	v_mov_b32_dpp v35, v36 quad_perm:[1,1,1,1] row_mask:0xf bank_mask:0xf
	v_mov_b32_dpp v37, v36 quad_perm:[2,2,2,2] row_mask:0xf bank_mask:0xf
	v_mov_b32_dpp v38, v36 quad_perm:[3,3,3,3] row_mask:0xf bank_mask:0xf
	s_addk_i32 s58, 0x80
	s_add_i32 s59, s59, 1
	v_mul_f32_e32 v34, v68, v34
	v_mul_f32_e32 v35, v69, v35
	v_mul_f32_e32 v37, v70, v37
	v_mul_f32_e32 v38, v71, v38
	v_mul_f32_e32 v34, v189, v34
	v_mul_f32_e32 v35, v189, v35
	v_mul_f32_e32 v37, v189, v37
	v_mul_f32_e32 v38, v189, v38
	v_mul_f32_e32 v34, v34, v72
	v_mul_f32_e32 v35, v35, v74
	v_mul_f32_e32 v37, v37, v73
	v_mul_f32_e32 v38, v38, v75
	v_pk_mul_f32 v[14:15], v[62:63], v[106:107]
	v_pk_mul_f32 v[12:13], v[60:61], v[104:105]
	v_pk_mul_f32 v[2:3], v[58:59], v[110:111]
	v_pk_mul_f32 v[0:1], v[56:57], v[108:109]
	v_pk_mul_f32 v[10:11], v[54:55], v[114:115]
	v_pk_mul_f32 v[8:9], v[52:53], v[112:113]
	v_pk_mul_f32 v[4:5], v[48:49], v[92:93]
	v_lshl_add_u64 v[190:191], v[190:191], 0, s[22:23]
	v_lshl_add_u64 v[198:199], v[198:199], 0, s[20:21]
	s_cmpk_eq_i32 s52, 0x400
	s_waitcnt vmcnt(16)
	v_mov_b32_e32 v247, v246
	v_mov_b32_e32 v248, v244
	v_mov_b32_e32 v250, v245
	v_mov_b32_e32 v249, v243
	v_cvt_pk_bf16_f32 v34, v34, s0
	v_cvt_pk_bf16_f32 v35, v35, s0
	v_cvt_pk_bf16_f32 v37, v37, s0
	v_cvt_pk_bf16_f32 v38, v38, s0
	global_store_short v[32:33], v34, off
	global_store_short v[32:33], v35, off offset:2048
	v_add_co_u32_e32 v32, vcc, s25, v32
	s_mov_b64 s[48:49], s[52:53]
	s_nop 0
	v_addc_co_u32_e32 v33, vcc, 0, v33, vcc
	global_store_short v[32:33], v37, off
	global_store_short v[32:33], v38, off offset:2048
	s_cbranch_scc1 .LBB0_2128
